# stack3 + P2: PARK constants job moved from bx==255 (conv-only, critical) to bx==0 (GEMM workgroup with slack)
# speedup vs baseline: 1.0001x; 1.0001x over previous
.LBB0_512:
	s_or_b64 exec, exec, s[2:3]
	v_lshl_add_u64 v[134:135], v[98:99], 0, v[102:103]
	v_lshl_add_u64 v[102:103], v[98:99], 0, v[118:119]
	s_waitcnt vmcnt(0)
	v_pk_mul_f32 v[118:119], v[18:19], v[120:121]
	v_lshl_add_u64 v[138:139], v[98:99], 0, v[106:107]
	v_lshl_add_u64 v[106:107], v[98:99], 0, v[110:111]
	v_lshlrev_b32_e32 v110, 16, v94
	v_and_b32_e32 v111, 0xffff0000, v94
	v_pk_fma_f32 v[118:119], v[30:31], v[132:133], v[118:119]
	v_lshl_add_u64 v[136:137], v[98:99], 0, v[104:105]
	v_pk_fma_f32 v[118:119], v[22:23], v[110:111], v[118:119]
	v_lshl_add_u64 v[104:105], v[98:99], 0, v[114:115]
	v_lshlrev_b32_e32 v114, 16, v90
	v_and_b32_e32 v115, 0xffff0000, v90
	v_pk_add_f32 v[118:119], v[26:27], v[118:119]
	v_lshl_add_u64 v[100:101], v[98:99], 0, v[122:123]
	v_pk_mul_f32 v[114:115], v[118:119], v[114:115]
	v_pk_mul_f32 v[118:119], v[20:21], v[116:117]
	v_lshl_add_u64 v[98:99], v[98:99], 0, v[124:125]
	v_lshlrev_b32_e32 v94, 16, v95
	v_and_b32_e32 v95, 0xffff0000, v95
	v_pk_fma_f32 v[118:119], v[32:33], v[130:131], v[118:119]
	v_pk_mul_f32 v[124:125], v[6:7], v[112:113]
	v_pk_fma_f32 v[118:119], v[24:25], v[94:95], v[118:119]
	v_lshlrev_b32_e32 v122, 16, v96
	v_and_b32_e32 v123, 0xffff0000, v96
	v_pk_fma_f32 v[124:125], v[10:11], v[128:129], v[124:125]
	v_lshlrev_b32_e32 v90, 16, v91
	v_and_b32_e32 v91, 0xffff0000, v91
	v_pk_add_f32 v[118:119], v[28:29], v[118:119]
	v_pk_fma_f32 v[124:125], v[2:3], v[122:123], v[124:125]
	v_pk_mul_f32 v[118:119], v[118:119], v[90:91]
	v_lshlrev_b32_e32 v90, 16, v92
	v_and_b32_e32 v91, 0xffff0000, v92
	v_pk_add_f32 v[124:125], v[14:15], v[124:125]
	v_lshlrev_b32_e32 v96, 16, v97
	v_pk_mul_f32 v[124:125], v[124:125], v[90:91]
	v_lshlrev_b32_e32 v90, 16, v93
	v_and_b32_e32 v91, 0xffff0000, v93
	v_pk_mul_f32 v[92:93], v[8:9], v[108:109]
	v_and_b32_e32 v97, 0xffff0000, v97
	v_pk_fma_f32 v[92:93], v[12:13], v[126:127], v[92:93]
	v_pk_mul_f32 v[112:113], v[10:11], v[112:113]
	v_pk_fma_f32 v[92:93], v[4:5], v[96:97], v[92:93]
	v_pk_fma_f32 v[112:113], v[6:7], v[122:123], v[112:113]
	v_pk_add_f32 v[92:93], v[16:17], v[92:93]
	s_nop 0
	v_pk_mul_f32 v[126:127], v[92:93], v[90:91]
	v_cvt_pk_bf16_f32 v90, v114, v115
	v_cvt_pk_bf16_f32 v91, v118, v119
	v_cvt_pk_bf16_f32 v92, v124, v125
	v_cvt_pk_bf16_f32 v93, v126, v127
	v_pk_mul_f32 v[114:115], v[30:31], v[120:121]
	global_store_dwordx4 v[134:135], v[90:93], off
	v_pk_fma_f32 v[114:115], v[18:19], v[110:111], v[114:115]
	s_nop 0
	v_lshlrev_b32_e32 v90, 16, v86
	v_and_b32_e32 v91, 0xffff0000, v86
	v_pk_fma_f32 v[114:115], v[22:23], v[90:91], v[114:115]
	v_lshlrev_b32_e32 v92, 16, v82
	v_and_b32_e32 v93, 0xffff0000, v82
	v_pk_add_f32 v[114:115], v[26:27], v[114:115]
	v_lshlrev_b32_e32 v86, 16, v87
	v_pk_mul_f32 v[92:93], v[114:115], v[92:93]
	v_pk_mul_f32 v[114:115], v[32:33], v[116:117]
	v_and_b32_e32 v87, 0xffff0000, v87
	v_pk_fma_f32 v[114:115], v[20:21], v[94:95], v[114:115]
	v_lshlrev_b32_e32 v116, 16, v88
	v_pk_fma_f32 v[114:115], v[24:25], v[86:87], v[114:115]
	v_and_b32_e32 v117, 0xffff0000, v88
	v_lshlrev_b32_e32 v82, 16, v83
	v_and_b32_e32 v83, 0xffff0000, v83
	v_pk_add_f32 v[114:115], v[28:29], v[114:115]
	v_pk_fma_f32 v[112:113], v[2:3], v[116:117], v[112:113]
	v_pk_mul_f32 v[114:115], v[114:115], v[82:83]
	v_lshlrev_b32_e32 v82, 16, v84
	v_and_b32_e32 v83, 0xffff0000, v84
	v_pk_add_f32 v[112:113], v[14:15], v[112:113]
	v_lshlrev_b32_e32 v88, 16, v89
	v_pk_mul_f32 v[112:113], v[112:113], v[82:83]
	v_lshlrev_b32_e32 v82, 16, v85
	v_and_b32_e32 v83, 0xffff0000, v85
	v_pk_mul_f32 v[84:85], v[12:13], v[108:109]
	v_and_b32_e32 v89, 0xffff0000, v89
	v_pk_fma_f32 v[84:85], v[8:9], v[96:97], v[84:85]
	s_nop 0
	v_pk_fma_f32 v[84:85], v[4:5], v[88:89], v[84:85]
	s_nop 0
	v_pk_add_f32 v[84:85], v[16:17], v[84:85]
	s_nop 0
	v_pk_mul_f32 v[108:109], v[84:85], v[82:83]
	v_cvt_pk_bf16_f32 v82, v92, v93
	v_cvt_pk_bf16_f32 v83, v114, v115
	v_cvt_pk_bf16_f32 v84, v112, v113
	v_cvt_pk_bf16_f32 v85, v108, v109
	v_pk_mul_f32 v[92:93], v[18:19], v[90:91]
	global_store_dwordx4 v[136:137], v[82:85], off
	v_pk_fma_f32 v[92:93], v[30:31], v[110:111], v[92:93]
	v_pk_mul_f32 v[108:109], v[6:7], v[116:117]
	v_lshlrev_b32_e32 v82, 16, v78
	v_and_b32_e32 v83, 0xffff0000, v78
	v_pk_fma_f32 v[92:93], v[22:23], v[82:83], v[92:93]
	v_lshlrev_b32_e32 v84, 16, v74
	v_and_b32_e32 v85, 0xffff0000, v74
	v_pk_add_f32 v[92:93], v[26:27], v[92:93]
	v_lshlrev_b32_e32 v78, 16, v79
	v_pk_mul_f32 v[84:85], v[92:93], v[84:85]
	v_pk_mul_f32 v[92:93], v[20:21], v[86:87]
	v_and_b32_e32 v79, 0xffff0000, v79
	v_pk_fma_f32 v[92:93], v[32:33], v[94:95], v[92:93]
	v_lshlrev_b32_e32 v94, 16, v80
	v_pk_fma_f32 v[92:93], v[24:25], v[78:79], v[92:93]
	v_and_b32_e32 v95, 0xffff0000, v80
	v_pk_fma_f32 v[108:109], v[10:11], v[122:123], v[108:109]
	v_lshlrev_b32_e32 v74, 16, v75
	v_and_b32_e32 v75, 0xffff0000, v75
	v_pk_add_f32 v[92:93], v[28:29], v[92:93]
	v_pk_fma_f32 v[108:109], v[2:3], v[94:95], v[108:109]
	v_pk_mul_f32 v[92:93], v[92:93], v[74:75]
	v_lshlrev_b32_e32 v74, 16, v76
	v_and_b32_e32 v75, 0xffff0000, v76
	v_pk_add_f32 v[108:109], v[14:15], v[108:109]
	v_lshlrev_b32_e32 v80, 16, v81
	v_pk_mul_f32 v[108:109], v[108:109], v[74:75]
	v_lshlrev_b32_e32 v74, 16, v77
	v_and_b32_e32 v75, 0xffff0000, v77
	v_pk_mul_f32 v[76:77], v[8:9], v[88:89]
	v_and_b32_e32 v81, 0xffff0000, v81
	v_pk_fma_f32 v[76:77], v[12:13], v[96:97], v[76:77]
	s_nop 0
	v_pk_fma_f32 v[76:77], v[4:5], v[80:81], v[76:77]
	s_nop 0
	v_pk_add_f32 v[76:77], v[16:17], v[76:77]
	s_nop 0
	v_pk_mul_f32 v[96:97], v[76:77], v[74:75]
	v_cvt_pk_bf16_f32 v74, v84, v85
	v_cvt_pk_bf16_f32 v75, v92, v93
	v_cvt_pk_bf16_f32 v76, v108, v109
	v_cvt_pk_bf16_f32 v77, v96, v97
	v_pk_mul_f32 v[84:85], v[18:19], v[82:83]
	global_store_dwordx4 v[138:139], v[74:77], off
	v_pk_fma_f32 v[84:85], v[30:31], v[90:91], v[84:85]
	v_pk_mul_f32 v[90:91], v[6:7], v[94:95]
	v_lshlrev_b32_e32 v74, 16, v70
	v_and_b32_e32 v75, 0xffff0000, v70
	v_pk_fma_f32 v[84:85], v[22:23], v[74:75], v[84:85]
	v_lshlrev_b32_e32 v76, 16, v66
	v_and_b32_e32 v77, 0xffff0000, v66
	v_pk_add_f32 v[84:85], v[26:27], v[84:85]
	v_lshlrev_b32_e32 v70, 16, v71
	v_pk_mul_f32 v[76:77], v[84:85], v[76:77]
	v_pk_mul_f32 v[84:85], v[20:21], v[78:79]
	v_and_b32_e32 v71, 0xffff0000, v71
	v_pk_fma_f32 v[84:85], v[32:33], v[86:87], v[84:85]
	v_lshlrev_b32_e32 v86, 16, v72
	v_pk_fma_f32 v[84:85], v[24:25], v[70:71], v[84:85]
	v_and_b32_e32 v87, 0xffff0000, v72
	v_pk_fma_f32 v[90:91], v[10:11], v[116:117], v[90:91]
	v_lshlrev_b32_e32 v66, 16, v67
	v_and_b32_e32 v67, 0xffff0000, v67
	v_pk_add_f32 v[84:85], v[28:29], v[84:85]
	v_pk_fma_f32 v[90:91], v[2:3], v[86:87], v[90:91]
	v_pk_mul_f32 v[84:85], v[84:85], v[66:67]
	v_lshlrev_b32_e32 v66, 16, v68
	v_and_b32_e32 v67, 0xffff0000, v68
	v_pk_add_f32 v[90:91], v[14:15], v[90:91]
	v_lshlrev_b32_e32 v72, 16, v73
	v_pk_mul_f32 v[90:91], v[90:91], v[66:67]
	v_lshlrev_b32_e32 v66, 16, v69
	v_and_b32_e32 v67, 0xffff0000, v69
	v_pk_mul_f32 v[68:69], v[8:9], v[80:81]
	v_and_b32_e32 v73, 0xffff0000, v73
	v_pk_fma_f32 v[68:69], v[12:13], v[88:89], v[68:69]
	s_nop 0
	v_pk_fma_f32 v[68:69], v[4:5], v[72:73], v[68:69]
	s_nop 0
	v_pk_add_f32 v[68:69], v[16:17], v[68:69]
	s_nop 0
	v_pk_mul_f32 v[88:89], v[68:69], v[66:67]
	v_cvt_pk_bf16_f32 v66, v76, v77
	v_cvt_pk_bf16_f32 v67, v84, v85
	v_cvt_pk_bf16_f32 v68, v90, v91
	v_cvt_pk_bf16_f32 v69, v88, v89
	v_pk_mul_f32 v[76:77], v[18:19], v[74:75]
	global_store_dwordx4 v[106:107], v[66:69], off
	v_pk_fma_f32 v[76:77], v[30:31], v[82:83], v[76:77]
	v_pk_mul_f32 v[82:83], v[6:7], v[86:87]
	v_lshlrev_b32_e32 v66, 16, v62
	v_and_b32_e32 v67, 0xffff0000, v62
	v_pk_fma_f32 v[76:77], v[22:23], v[66:67], v[76:77]
	v_lshlrev_b32_e32 v68, 16, v58
	v_and_b32_e32 v69, 0xffff0000, v58
	v_pk_add_f32 v[76:77], v[26:27], v[76:77]
	v_lshlrev_b32_e32 v62, 16, v63
	v_pk_mul_f32 v[68:69], v[76:77], v[68:69]
	v_pk_mul_f32 v[76:77], v[20:21], v[70:71]
	v_and_b32_e32 v63, 0xffff0000, v63
	v_pk_fma_f32 v[76:77], v[32:33], v[78:79], v[76:77]
	v_lshlrev_b32_e32 v78, 16, v64
	v_pk_fma_f32 v[76:77], v[24:25], v[62:63], v[76:77]
	v_and_b32_e32 v79, 0xffff0000, v64
	v_pk_fma_f32 v[82:83], v[10:11], v[94:95], v[82:83]
	v_lshlrev_b32_e32 v58, 16, v59
	v_and_b32_e32 v59, 0xffff0000, v59
	v_pk_add_f32 v[76:77], v[28:29], v[76:77]
	v_pk_fma_f32 v[82:83], v[2:3], v[78:79], v[82:83]
	v_pk_mul_f32 v[76:77], v[76:77], v[58:59]
	v_lshlrev_b32_e32 v58, 16, v60
	v_and_b32_e32 v59, 0xffff0000, v60
	v_pk_add_f32 v[82:83], v[14:15], v[82:83]
	v_lshlrev_b32_e32 v64, 16, v65
	v_pk_mul_f32 v[82:83], v[82:83], v[58:59]
	v_lshlrev_b32_e32 v58, 16, v61
	v_and_b32_e32 v59, 0xffff0000, v61
	v_pk_mul_f32 v[60:61], v[8:9], v[72:73]
	v_and_b32_e32 v65, 0xffff0000, v65
	v_pk_fma_f32 v[60:61], v[12:13], v[80:81], v[60:61]
	s_nop 0
	v_pk_fma_f32 v[60:61], v[4:5], v[64:65], v[60:61]
	s_nop 0
	v_pk_add_f32 v[60:61], v[16:17], v[60:61]
	s_nop 0
	v_pk_mul_f32 v[80:81], v[60:61], v[58:59]
	v_cvt_pk_bf16_f32 v58, v68, v69
	v_cvt_pk_bf16_f32 v59, v76, v77
	v_cvt_pk_bf16_f32 v60, v82, v83
	v_cvt_pk_bf16_f32 v61, v80, v81
	v_pk_mul_f32 v[68:69], v[18:19], v[66:67]
	global_store_dwordx4 v[104:105], v[58:61], off
	v_pk_fma_f32 v[68:69], v[30:31], v[74:75], v[68:69]
	v_pk_mul_f32 v[74:75], v[6:7], v[78:79]
	v_lshlrev_b32_e32 v58, 16, v54
	v_and_b32_e32 v59, 0xffff0000, v54
	v_pk_fma_f32 v[68:69], v[22:23], v[58:59], v[68:69]
	v_lshlrev_b32_e32 v60, 16, v50
	v_and_b32_e32 v61, 0xffff0000, v50
	v_pk_add_f32 v[68:69], v[26:27], v[68:69]
	v_lshlrev_b32_e32 v54, 16, v55
	v_pk_mul_f32 v[60:61], v[68:69], v[60:61]
	v_pk_mul_f32 v[68:69], v[20:21], v[62:63]
	v_and_b32_e32 v55, 0xffff0000, v55
	v_pk_fma_f32 v[68:69], v[32:33], v[70:71], v[68:69]
	v_lshlrev_b32_e32 v70, 16, v56
	v_pk_fma_f32 v[68:69], v[24:25], v[54:55], v[68:69]
	v_and_b32_e32 v71, 0xffff0000, v56
	v_pk_fma_f32 v[74:75], v[10:11], v[86:87], v[74:75]
	v_lshlrev_b32_e32 v50, 16, v51
	v_and_b32_e32 v51, 0xffff0000, v51
	v_pk_add_f32 v[68:69], v[28:29], v[68:69]
	v_pk_fma_f32 v[74:75], v[2:3], v[70:71], v[74:75]
	v_pk_mul_f32 v[68:69], v[68:69], v[50:51]
	v_lshlrev_b32_e32 v50, 16, v52
	v_and_b32_e32 v51, 0xffff0000, v52
	v_pk_add_f32 v[74:75], v[14:15], v[74:75]
	v_lshlrev_b32_e32 v56, 16, v57
	v_pk_mul_f32 v[74:75], v[74:75], v[50:51]
	v_lshlrev_b32_e32 v50, 16, v53
	v_and_b32_e32 v51, 0xffff0000, v53
	v_pk_mul_f32 v[52:53], v[8:9], v[64:65]
	v_and_b32_e32 v57, 0xffff0000, v57
	v_pk_fma_f32 v[52:53], v[12:13], v[72:73], v[52:53]
	s_nop 0
	v_pk_fma_f32 v[52:53], v[4:5], v[56:57], v[52:53]
	s_nop 0
	v_pk_add_f32 v[52:53], v[16:17], v[52:53]
	s_nop 0
	v_pk_mul_f32 v[72:73], v[52:53], v[50:51]
	v_cvt_pk_bf16_f32 v50, v60, v61
	v_cvt_pk_bf16_f32 v51, v68, v69
	v_cvt_pk_bf16_f32 v52, v74, v75
	v_cvt_pk_bf16_f32 v53, v72, v73
	v_pk_mul_f32 v[60:61], v[18:19], v[58:59]
	global_store_dwordx4 v[102:103], v[50:53], off
	v_pk_fma_f32 v[60:61], v[30:31], v[66:67], v[60:61]
	v_pk_mul_f32 v[66:67], v[6:7], v[70:71]
	v_lshlrev_b32_e32 v50, 16, v46
	v_and_b32_e32 v51, 0xffff0000, v46
	v_pk_fma_f32 v[60:61], v[22:23], v[50:51], v[60:61]
	v_lshlrev_b32_e32 v52, 16, v42
	v_and_b32_e32 v53, 0xffff0000, v42
	v_pk_add_f32 v[60:61], v[26:27], v[60:61]
	v_lshlrev_b32_e32 v46, 16, v47
	v_pk_mul_f32 v[52:53], v[60:61], v[52:53]
	v_pk_mul_f32 v[60:61], v[20:21], v[54:55]
	v_and_b32_e32 v47, 0xffff0000, v47
	v_pk_fma_f32 v[60:61], v[32:33], v[62:63], v[60:61]
	v_lshlrev_b32_e32 v62, 16, v48
	v_pk_fma_f32 v[60:61], v[24:25], v[46:47], v[60:61]
	v_and_b32_e32 v63, 0xffff0000, v48
	v_pk_fma_f32 v[66:67], v[10:11], v[78:79], v[66:67]
	v_lshlrev_b32_e32 v42, 16, v43
	v_and_b32_e32 v43, 0xffff0000, v43
	v_pk_add_f32 v[60:61], v[28:29], v[60:61]
	v_pk_fma_f32 v[66:67], v[2:3], v[62:63], v[66:67]
	v_pk_mul_f32 v[60:61], v[60:61], v[42:43]
	v_lshlrev_b32_e32 v42, 16, v44
	v_and_b32_e32 v43, 0xffff0000, v44
	v_pk_add_f32 v[66:67], v[14:15], v[66:67]
	v_lshlrev_b32_e32 v48, 16, v49
	v_pk_mul_f32 v[66:67], v[66:67], v[42:43]
	v_lshlrev_b32_e32 v42, 16, v45
	v_and_b32_e32 v43, 0xffff0000, v45
	v_pk_mul_f32 v[44:45], v[8:9], v[56:57]
	v_and_b32_e32 v49, 0xffff0000, v49
	v_pk_fma_f32 v[44:45], v[12:13], v[64:65], v[44:45]
	v_pk_mul_f32 v[18:19], v[18:19], v[50:51]
	v_pk_fma_f32 v[44:45], v[4:5], v[48:49], v[44:45]
	v_pk_fma_f32 v[18:19], v[30:31], v[58:59], v[18:19]
	v_pk_add_f32 v[44:45], v[16:17], v[44:45]
	v_pk_mul_f32 v[20:21], v[20:21], v[46:47]
	v_pk_mul_f32 v[64:65], v[44:45], v[42:43]
	v_cvt_pk_bf16_f32 v42, v52, v53
	v_cvt_pk_bf16_f32 v43, v60, v61
	v_cvt_pk_bf16_f32 v44, v66, v67
	v_cvt_pk_bf16_f32 v45, v64, v65
	global_store_dwordx4 v[100:101], v[42:45], off
	v_pk_fma_f32 v[20:21], v[32:33], v[54:55], v[20:21]
	v_pk_mul_f32 v[6:7], v[6:7], v[62:63]
	v_lshlrev_b32_e32 v42, 16, v34
	v_and_b32_e32 v43, 0xffff0000, v34
	v_pk_fma_f32 v[18:19], v[22:23], v[42:43], v[18:19]
	v_lshlrev_b32_e32 v22, 16, v35
	v_and_b32_e32 v23, 0xffff0000, v35
	v_pk_fma_f32 v[20:21], v[24:25], v[22:23], v[20:21]
	v_lshlrev_b32_e32 v22, 16, v36
	v_and_b32_e32 v23, 0xffff0000, v36
	v_pk_fma_f32 v[6:7], v[10:11], v[70:71], v[6:7]
	v_lshlrev_b32_e32 v24, 16, v40
	v_pk_fma_f32 v[2:3], v[2:3], v[22:23], v[6:7]
	v_and_b32_e32 v25, 0xffff0000, v40
	v_pk_add_f32 v[2:3], v[14:15], v[2:3]
	v_pk_mul_f32 v[8:9], v[8:9], v[48:49]
	v_pk_mul_f32 v[6:7], v[2:3], v[24:25]
	v_lshlrev_b32_e32 v2, 16, v37
	v_and_b32_e32 v3, 0xffff0000, v37
	v_pk_fma_f32 v[8:9], v[12:13], v[56:57], v[8:9]
	v_lshlrev_b32_e32 v44, 16, v38
	v_pk_fma_f32 v[2:3], v[4:5], v[2:3], v[8:9]
	v_and_b32_e32 v45, 0xffff0000, v38
	v_pk_add_f32 v[18:19], v[26:27], v[18:19]
	v_lshlrev_b32_e32 v26, 16, v39
	v_and_b32_e32 v27, 0xffff0000, v39
	v_pk_add_f32 v[20:21], v[28:29], v[20:21]
	v_lshlrev_b32_e32 v10, 16, v41
	v_and_b32_e32 v11, 0xffff0000, v41
	v_pk_add_f32 v[2:3], v[16:17], v[2:3]
	v_pk_mul_f32 v[18:19], v[18:19], v[44:45]
	v_pk_mul_f32 v[20:21], v[20:21], v[26:27]
	v_pk_mul_f32 v[8:9], v[2:3], v[10:11]
	v_cvt_pk_bf16_f32 v2, v18, v19
	v_cvt_pk_bf16_f32 v3, v20, v21
	v_cvt_pk_bf16_f32 v4, v6, v7
	v_cvt_pk_bf16_f32 v5, v8, v9
	global_store_dwordx4 v[98:99], v[2:5], off
	s_mov_b32 s0, 0
	s_cmp_lg_u32 s78, s0
	s_cbranch_scc0 .LBB0_515
	s_branch .LBB0_516
.LBB0_513:
.LBB0_514:
	s_mov_b32 s0, 0
	s_cmp_lg_u32 s78, s0
	s_cbranch_scc1 .LBB0_516
